# grid-barrier acquire moved ahead: wave 0 issues buffer_inv sc1 before the seam's entry barrier, the invalidates behind the flag waits deleted
# speedup vs baseline: 1.0114x; 1.0114x over previous
; #define SEAM(k) do { if (IN(k) && IN((k) + 1)) xcd_barrier(bar); } while (0)
; __device__ __forceinline__ void xcd_barrier(const XcdBarrier& b) {
;     asm volatile("s_waitcnt vmcnt(0)" ::: "memory");
;     __syncthreads();
;     if (threadIdx.x == 0) {
;         unsigned* bar = b.bar;
;         __builtin_amdgcn_s_waitcnt(0);
;         unsigned nloc = b.st[0], nx = b.st[1];
;         if (nloc == 0u) { xcd_barrier_complete(bar, b.x, nloc, nx); b.st[0] = nloc; b.st[1] = nx; }
; __global__ void __launch_bounds__(512, 2) mk_fwd(Args args) {
;     ...
;     if (IN(0)) { p0_prologue(F); } SEAM(0);
.LBB0_94:
	s_cmp_gt_i32 s91, 1
	s_cselect_b64 s[0:1], -1, 0
	s_and_b64 s[2:3], s[6:7], s[0:1]
	s_andn2_b64 vcc, exec, s[2:3]
	s_cbranch_vccnz .LBB0_148
	s_cmp_lg_u32 s98, 0
	s_cbranch_scc1 .Leinv0
	buffer_inv sc1
.Leinv0:
	s_waitcnt vmcnt(0)
	s_waitcnt lgkmcnt(0)
	s_barrier
	s_mov_b64 s[2:3], exec
	v_readlane_b32 s4, v254, 37
	v_readlane_b32 s5, v254, 38
	s_and_b64 s[4:5], s[2:3], s[4:5]
	s_mov_b64 exec, s[4:5]
	s_cbranch_execz .LBB0_147
	s_add_i32 s4, 0, 0x27f20
	v_mov_b32_e32 v1, s4
	s_waitcnt vmcnt(0) expcnt(0) lgkmcnt(0)
	ds_read_b32 v3, v1
	s_add_i32 s4, 0, 0x27f24
	v_mov_b32_e32 v1, s4
	ds_read_b32 v1, v1
	s_waitcnt lgkmcnt(1)
	v_cmp_ne_u32_e32 vcc, 0, v3
	s_cbranch_vccnz .LBB0_111
	v_readlane_b32 s4, v254, 0
	v_readlane_b32 s5, v254, 1
	s_load_dwordx2 s[8:9], s[4:5], 0x4
	v_readlane_b32 s10, v254, 34
	v_readlane_b32 s11, v254, 35
	s_add_u32 s4, s10, 0x1000
	s_addc_u32 s5, s11, 0
	s_add_u32 s6, s10, 0x1100
	s_addc_u32 s7, s11, 0
	s_waitcnt lgkmcnt(0)
	s_mul_i32 s18, s8, s96
	s_add_u32 s8, s10, 0x1200
	s_mul_i32 s18, s18, s9
	s_addc_u32 s9, s11, 0
	s_add_u32 s10, s10, 0x1300
	s_addc_u32 s11, s11, 0
	s_mov_b32 s19, 1
	v_mov_b32_e32 v17, 0
	s_branch .LBB0_99

; __device__ __forceinline__ unsigned xb_ld(unsigned* p)              { return __hip_atomic_load(p, __ATOMIC_RELAXED, __HIP_MEMORY_SCOPE_AGENT); }
; #define XB_SPIN(cond, bar) do { unsigned _sp = 0; while (cond) { __builtin_amdgcn_s_sleep(1); \
;     if ((++_sp & 255u) == 0u) { if (xb_ld(&(bar)[XB_TMO])) break; if (_sp > XB_SPIN_CAP) { atomicAdd(&(bar)[XB_TMO], 1u); break; } } } } while (0)
; __device__ __forceinline__ void xcd_barrier(const XcdBarrier& b) {
;     ...
;             XB_SPIN(xb_ld(&bar[XB_XGEN(b.x)]) == gen, bar);
;             __builtin_amdgcn_fence(__ATOMIC_ACQUIRE, "agent");
;             asm volatile("s_waitcnt vmcnt(0)" ::: "memory");
.LBB0_126:
	s_or_b64 exec, exec, s[8:9]
	s_waitcnt vmcnt(0)
	s_waitcnt vmcnt(0)

; __device__ __forceinline__ unsigned xb_ld(unsigned* p)              { return __hip_atomic_load(p, __ATOMIC_RELAXED, __HIP_MEMORY_SCOPE_AGENT); }
; __device__ __forceinline__ unsigned xb_add(unsigned* p, unsigned v) { return __hip_atomic_fetch_add(p, v, __ATOMIC_RELAXED, __HIP_MEMORY_SCOPE_AGENT); }
; #define XB_SPIN(cond, bar) do { unsigned _sp = 0; while (cond) { __builtin_amdgcn_s_sleep(1); \
;     if ((++_sp & 255u) == 0u) { if (xb_ld(&(bar)[XB_TMO])) break; if (_sp > XB_SPIN_CAP) { atomicAdd(&(bar)[XB_TMO], 1u); break; } } } } while (0)
; __device__ __forceinline__ void xcd_barrier(const XcdBarrier& b) {
;     ...
;             if (og + 1u == (tg + 1u) * nx) xb_add(&bar[XB_TOPGEN], 1u);
;             else XB_SPIN(xb_ld(&bar[XB_TOPGEN]) == tg, bar);
;             __builtin_amdgcn_fence(__ATOMIC_ACQUIRE, "agent");
;             xb_add(&bar[XB_XGEN(b.x)], 1u);
.LBB0_144:
	s_or_b64 exec, exec, s[6:7]
	s_mov_b64 s[6:7], exec
	v_mbcnt_lo_u32_b32 v1, s6, 0
	v_mbcnt_hi_u32_b32 v1, s7, v1
	v_cmp_eq_u32_e32 vcc, 0, v1
	s_waitcnt vmcnt(0)
	s_and_saveexec_b64 s[8:9], vcc
	s_cbranch_execz .LBB0_146
	s_bcnt1_i32_b64 s6, s[6:7]
	v_mov_b32_e32 v1, 0x2000
	v_mov_b32_e32 v2, s6
	global_atomic_add v1, v2, s[4:5] offset:1024

; #define SEAM(k) do { if (IN(k) && IN((k) + 1)) xcd_barrier(bar); } while (0)
; __device__ __forceinline__ void xcd_barrier(const XcdBarrier& b) {
;     asm volatile("s_waitcnt vmcnt(0)" ::: "memory");
;     __syncthreads();
;     if (threadIdx.x == 0) {
;         unsigned* bar = b.bar;
;         __builtin_amdgcn_s_waitcnt(0);
;         unsigned nloc = b.st[0], nx = b.st[1];
;         if (nloc == 0u) { xcd_barrier_complete(bar, b.x, nloc, nx); b.st[0] = nloc; b.st[1] = nx; }
; __global__ void __launch_bounds__(512, 2) mk_fwd(Args args) {
;     ...
;             pg8::gemm_phase<EpiProjConv, pg8::GeomPlain, pg8::ChunkOrder, true>(F.lds, g, S, E); } } SEAM(1);
.LBB0_1796:
	s_cmp_gt_u32 s91, 2
	s_cselect_b64 s[0:1], -1, 0
	s_and_b64 s[0:1], s[28:29], s[0:1]
	s_andn2_b64 vcc, exec, s[0:1]
	s_cbranch_vccnz .LBB0_1850
	s_cmp_lg_u32 s98, 0
	s_cbranch_scc1 .Leinv1
	buffer_inv sc1
.Leinv1:
	s_waitcnt vmcnt(0)
	s_waitcnt lgkmcnt(0)
	s_barrier
	s_mov_b64 s[0:1], exec
	v_readlane_b32 s2, v254, 37
	v_readlane_b32 s3, v254, 38
	s_and_b64 s[2:3], s[0:1], s[2:3]
	s_mov_b64 exec, s[2:3]
	s_cbranch_execz .LBB0_1849
	s_add_i32 s2, 0, 0x27f20
	v_mov_b32_e32 v1, s2
	s_waitcnt vmcnt(0) expcnt(0) lgkmcnt(0)
	ds_read_b32 v3, v1
	s_add_i32 s2, 0, 0x27f24
	v_mov_b32_e32 v1, s2
	ds_read_b32 v1, v1
	s_waitcnt lgkmcnt(1)
	v_cmp_ne_u32_e32 vcc, 0, v3
	s_cbranch_vccnz .LBB0_1813
	v_readlane_b32 s2, v254, 0
	v_readlane_b32 s3, v254, 1
	s_load_dwordx2 s[6:7], s[2:3], 0x4
	v_readlane_b32 s8, v254, 34
	v_readlane_b32 s9, v254, 35
	s_add_u32 s2, s8, 0x1000
	s_addc_u32 s3, s9, 0
	s_add_u32 s4, s8, 0x1100
	s_addc_u32 s5, s9, 0
	s_waitcnt lgkmcnt(0)
	s_mul_i32 s16, s6, s96
	s_add_u32 s6, s8, 0x1200
	s_mul_i32 s16, s16, s7
	s_addc_u32 s7, s9, 0
	s_add_u32 s8, s8, 0x1300
	s_addc_u32 s9, s9, 0
	s_mov_b32 s17, 1
	v_mov_b32_e32 v17, 0
	s_branch .LBB0_1801

; __device__ __forceinline__ unsigned xb_ld(unsigned* p)              { return __hip_atomic_load(p, __ATOMIC_RELAXED, __HIP_MEMORY_SCOPE_AGENT); }
; #define XB_SPIN(cond, bar) do { unsigned _sp = 0; while (cond) { __builtin_amdgcn_s_sleep(1); \
;     if ((++_sp & 255u) == 0u) { if (xb_ld(&(bar)[XB_TMO])) break; if (_sp > XB_SPIN_CAP) { atomicAdd(&(bar)[XB_TMO], 1u); break; } } } } while (0)
; __device__ __forceinline__ void xcd_barrier(const XcdBarrier& b) {
;     ...
;             XB_SPIN(xb_ld(&bar[XB_XGEN(b.x)]) == gen, bar);
;             __builtin_amdgcn_fence(__ATOMIC_ACQUIRE, "agent");
;             asm volatile("s_waitcnt vmcnt(0)" ::: "memory");
.LBB0_1828:
	s_or_b64 exec, exec, s[6:7]
	s_waitcnt vmcnt(0)
	s_waitcnt vmcnt(0)

; __device__ __forceinline__ unsigned xb_ld(unsigned* p)              { return __hip_atomic_load(p, __ATOMIC_RELAXED, __HIP_MEMORY_SCOPE_AGENT); }
; __device__ __forceinline__ unsigned xb_add(unsigned* p, unsigned v) { return __hip_atomic_fetch_add(p, v, __ATOMIC_RELAXED, __HIP_MEMORY_SCOPE_AGENT); }
; #define XB_SPIN(cond, bar) do { unsigned _sp = 0; while (cond) { __builtin_amdgcn_s_sleep(1); \
;     if ((++_sp & 255u) == 0u) { if (xb_ld(&(bar)[XB_TMO])) break; if (_sp > XB_SPIN_CAP) { atomicAdd(&(bar)[XB_TMO], 1u); break; } } } } while (0)
; __device__ __forceinline__ void xcd_barrier(const XcdBarrier& b) {
;     ...
;             if (og + 1u == (tg + 1u) * nx) xb_add(&bar[XB_TOPGEN], 1u);
;             else XB_SPIN(xb_ld(&bar[XB_TOPGEN]) == tg, bar);
;             __builtin_amdgcn_fence(__ATOMIC_ACQUIRE, "agent");
;             xb_add(&bar[XB_XGEN(b.x)], 1u);
.LBB0_1846:
	s_or_b64 exec, exec, s[4:5]
	s_mov_b64 s[4:5], exec
	v_mbcnt_lo_u32_b32 v1, s4, 0
	v_mbcnt_hi_u32_b32 v1, s5, v1
	v_cmp_eq_u32_e32 vcc, 0, v1
	s_waitcnt vmcnt(0)
	s_and_saveexec_b64 s[6:7], vcc
	s_cbranch_execz .LBB0_1848
	s_bcnt1_i32_b64 s4, s[4:5]
	v_mov_b32_e32 v1, 0x2000
	v_mov_b32_e32 v2, s4
	global_atomic_add v1, v2, s[2:3] offset:1024

; #define SEAM(k) do { if (IN(k) && IN((k) + 1)) xcd_barrier(bar); } while (0)
; __device__ __forceinline__ void xcd_barrier(const XcdBarrier& b) {
;     asm volatile("s_waitcnt vmcnt(0)" ::: "memory");
;     __syncthreads();
; __global__ void __launch_bounds__(512, 2) mk_fwd(Args args) {
;     ...
;     } SEAM(3);
.LBB0_1950:
	s_cmp_gt_i32 s91, 4
	s_cselect_b64 s[0:1], -1, 0
	s_and_b64 s[2:3], s[2:3], s[0:1]
	s_andn2_b64 vcc, exec, s[2:3]
	s_cbranch_vccnz .LBB0_2004
	s_cmp_lg_u32 s98, 0
	s_cbranch_scc1 .Leinv2
	buffer_inv sc1

; #define SEAM(k) do { if (IN(k) && IN((k) + 1)) xcd_barrier(bar); } while (0)
; __device__ __forceinline__ void xcd_barrier(const XcdBarrier& b) {
;     asm volatile("s_waitcnt vmcnt(0)" ::: "memory");
;     __syncthreads();
; __global__ void __launch_bounds__(512, 2) mk_fwd(Args args) {
;     ...
;     if (IN(4)) { p4_scan(F); } SEAM(4);
.LBB0_2040:
	s_cmp_gt_i32 s91, 5
	s_cselect_b64 s[0:1], -1, 0
	s_and_b64 s[2:3], s[22:23], s[0:1]
	s_andn2_b64 vcc, exec, s[2:3]
	s_cbranch_vccnz .LBB0_2094
	s_cmp_lg_u32 s98, 0
	s_cbranch_scc1 .Leinv3
	buffer_inv sc1

; __device__ __forceinline__ void xcd_barrier(const XcdBarrier& b) {
;     asm volatile("s_waitcnt vmcnt(0)" ::: "memory");
;     __syncthreads();
; __global__ void __launch_bounds__(512, 2) mk_fwd(Args args) {
;     ...
;         xcd_barrier(bar);
.LBB0_2110:
	s_cmp_lg_u32 s98, 0
	s_cbranch_scc1 .Leinv4
	buffer_inv sc1

; __device__ __forceinline__ unsigned xb_ld(unsigned* p)              { return __hip_atomic_load(p, __ATOMIC_RELAXED, __HIP_MEMORY_SCOPE_AGENT); }
; #define XB_SPIN(cond, bar) do { unsigned _sp = 0; while (cond) { __builtin_amdgcn_s_sleep(1); \
;     if ((++_sp & 255u) == 0u) { if (xb_ld(&(bar)[XB_TMO])) break; if (_sp > XB_SPIN_CAP) { atomicAdd(&(bar)[XB_TMO], 1u); break; } } } } while (0)
; __device__ __forceinline__ void xcd_barrier(const XcdBarrier& b) {
;     ...
;             XB_SPIN(xb_ld(&bar[XB_XGEN(b.x)]) == gen, bar);
;             __builtin_amdgcn_fence(__ATOMIC_ACQUIRE, "agent");
;             asm volatile("s_waitcnt vmcnt(0)" ::: "memory");
.LBB0_2141:
	s_or_b64 exec, exec, s[12:13]
	s_waitcnt vmcnt(0)
	s_waitcnt vmcnt(0)

; __device__ __forceinline__ unsigned xb_ld(unsigned* p)              { return __hip_atomic_load(p, __ATOMIC_RELAXED, __HIP_MEMORY_SCOPE_AGENT); }
; __device__ __forceinline__ unsigned xb_add(unsigned* p, unsigned v) { return __hip_atomic_fetch_add(p, v, __ATOMIC_RELAXED, __HIP_MEMORY_SCOPE_AGENT); }
; #define XB_SPIN(cond, bar) do { unsigned _sp = 0; while (cond) { __builtin_amdgcn_s_sleep(1); \
;     if ((++_sp & 255u) == 0u) { if (xb_ld(&(bar)[XB_TMO])) break; if (_sp > XB_SPIN_CAP) { atomicAdd(&(bar)[XB_TMO], 1u); break; } } } } while (0)
; __device__ __forceinline__ void xcd_barrier(const XcdBarrier& b) {
;     ...
;             if (og + 1u == (tg + 1u) * nx) xb_add(&bar[XB_TOPGEN], 1u);
;             else XB_SPIN(xb_ld(&bar[XB_TOPGEN]) == tg, bar);
;             __builtin_amdgcn_fence(__ATOMIC_ACQUIRE, "agent");
;             xb_add(&bar[XB_XGEN(b.x)], 1u);
.LBB0_2159:
	s_or_b64 exec, exec, s[10:11]
	s_mov_b64 s[10:11], exec
	v_mbcnt_lo_u32_b32 v1, s10, 0
	v_mbcnt_hi_u32_b32 v1, s11, v1
	v_cmp_eq_u32_e32 vcc, 0, v1
	s_waitcnt vmcnt(0)
	s_and_saveexec_b64 s[12:13], vcc
	s_cbranch_execz .LBB0_2161
	s_bcnt1_i32_b64 s7, s[10:11]
	v_mov_b32_e32 v1, 0x2000
	v_mov_b32_e32 v2, s7
	global_atomic_add v1, v2, s[4:5] offset:1024

; #define SEAM(k) do { if (IN(k) && IN((k) + 1)) xcd_barrier(bar); } while (0)
; __device__ __forceinline__ void xcd_barrier(const XcdBarrier& b) {
;     asm volatile("s_waitcnt vmcnt(0)" ::: "memory");
;     __syncthreads();
;     if (threadIdx.x == 0) {
;         unsigned* bar = b.bar;
;         __builtin_amdgcn_s_waitcnt(0);
;         unsigned nloc = b.st[0], nx = b.st[1];
;         if (nloc == 0u) { xcd_barrier_complete(bar, b.x, nloc, nx); b.st[0] = nloc; b.st[1] = nx; }
; __global__ void __launch_bounds__(512, 2) mk_fwd(Args args) {
;     ...
;         rotq_rows_i8<2, true>(WSP(bf16_t, WS_CAT), WSP(unsigned char, WS_CATQ), WSP(float, WS_SA2), M, F.wave * F.G + (int)blockIdx.x, F.G * 8, F.lane, WSP(float, WS_SSQRG)); } SEAM(5);
.LBB0_2167:
	s_cmp_gt_i32 s91, 6
	s_cselect_b64 s[2:3], -1, 0
	s_and_b64 s[0:1], s[0:1], s[2:3]
	s_andn2_b64 vcc, exec, s[0:1]
	s_cbranch_vccnz .LBB0_2221
	s_cmp_lg_u32 s98, 0
	s_cbranch_scc1 .Leinv5
	buffer_inv sc1
.Leinv5:
	s_waitcnt vmcnt(0)
	s_waitcnt lgkmcnt(0)
	s_barrier
	s_mov_b64 s[0:1], exec
	v_readlane_b32 s4, v254, 37
	v_readlane_b32 s5, v254, 38
	s_and_b64 s[4:5], s[0:1], s[4:5]
	s_mov_b64 exec, s[4:5]
	s_cbranch_execz .LBB0_2220
	s_add_i32 s4, 0, 0x27f20
	v_mov_b32_e32 v1, s4
	s_waitcnt vmcnt(0) expcnt(0) lgkmcnt(0)
	ds_read_b32 v3, v1
	s_add_i32 s4, 0, 0x27f24
	v_mov_b32_e32 v1, s4
	ds_read_b32 v1, v1
	s_waitcnt lgkmcnt(1)
	v_cmp_ne_u32_e32 vcc, 0, v3
	s_cbranch_vccnz .LBB0_2184
	v_readlane_b32 s4, v254, 0
	v_readlane_b32 s5, v254, 1
	s_load_dwordx2 s[8:9], s[4:5], 0x4
	v_readlane_b32 s10, v254, 34
	v_readlane_b32 s11, v254, 35
	s_add_u32 s4, s10, 0x1000
	s_addc_u32 s5, s11, 0
	s_add_u32 s6, s10, 0x1100
	s_addc_u32 s7, s11, 0
	s_waitcnt lgkmcnt(0)
	s_mul_i32 s18, s8, s96
	s_add_u32 s8, s10, 0x1200
	s_mul_i32 s18, s18, s9
	s_addc_u32 s9, s11, 0
	s_add_u32 s10, s10, 0x1300
	s_addc_u32 s11, s11, 0
	s_mov_b32 s19, 1
	v_mov_b32_e32 v17, 0
	s_branch .LBB0_2172

; #define SEAM(k) do { if (IN(k) && IN((k) + 1)) xcd_barrier(bar); } while (0)
; __device__ __forceinline__ void xcd_barrier(const XcdBarrier& b) {
;     asm volatile("s_waitcnt vmcnt(0)" ::: "memory");
;     __syncthreads();
; __global__ void __launch_bounds__(512, 2) mk_fwd(Args args) {
;     ...
;             pg8::gemm_phase<EpiPartQ, pg8::GeomSplit, pg8::SplitOrder, true, true>(F.lds, g2, S2, E2); } } SEAM(6);
.LBB0_2247:
	s_cmp_gt_i32 s91, 7
	s_cselect_b64 s[2:3], -1, 0
	s_and_b64 s[0:1], s[0:1], s[2:3]
	s_andn2_b64 vcc, exec, s[0:1]
	s_cbranch_vccnz .LBB0_2301
	s_cmp_lg_u32 s98, 0
	s_cbranch_scc1 .Leinv6
	buffer_inv sc1

; #define SEAM(k) do { if (IN(k) && IN((k) + 1)) xcd_barrier(bar); } while (0)
; __device__ __forceinline__ void xcd_barrier(const XcdBarrier& b) {
;     asm volatile("s_waitcnt vmcnt(0)" ::: "memory");
;     __syncthreads();
; __global__ void __launch_bounds__(512, 2) mk_fwd(Args args) {
;     ...
;         if (F.G != 256) rotq_rows_i8(WSP(bf16_t, WS_BT4), WSP(unsigned char, WS_BT4Q), WSP(float, WS_SW4), DM, blockIdx.x * 8 + F.wave, F.G * 8, F.lane); } SEAM(7);
.LBB0_2454:
	s_cmp_gt_i32 s91, 8
	s_cselect_b64 s[0:1], -1, 0
	s_and_b64 s[2:3], s[18:19], s[0:1]
	s_andn2_b64 vcc, exec, s[2:3]
	s_cbranch_vccnz .LBB0_2508
	s_cmp_lg_u32 s98, 0
	s_cbranch_scc1 .Leinv7
	buffer_inv sc1

; #define SEAM(k) do { if (IN(k) && IN((k) + 1)) xcd_barrier(bar); } while (0)
; __device__ __forceinline__ void xcd_barrier(const XcdBarrier& b) {
;     asm volatile("s_waitcnt vmcnt(0)" ::: "memory");
;     __syncthreads();
; __global__ void __launch_bounds__(512, 2) mk_fwd(Args args) {
;     ...
;         if (F.G == 256 && blockIdx.x >= G3_BUSY) rotq_rows_i8(WSP(bf16_t, WS_BT4), WSP(unsigned char, WS_BT4Q), WSP(float, WS_SW4), DM, ((int)blockIdx.x - G3_BUSY) * 8 + F.wave, (256 - G3_BUSY) * 8, F.lane); } SEAM(8);
.LBB0_2744:
	s_cmp_gt_i32 s91, 9
	s_cselect_b64 s[2:3], -1, 0
	s_and_b64 s[0:1], s[20:21], s[2:3]
	s_andn2_b64 vcc, exec, s[0:1]
	v_readlane_b32 s66, v254, 40
	s_cbranch_vccnz .LBB0_2798
	s_cmp_lg_u32 s98, 0
	s_cbranch_scc1 .Leinv8
	buffer_inv sc1

; #define SEAM(k) do { if (IN(k) && IN((k) + 1)) xcd_barrier(bar); } while (0)
; __device__ __forceinline__ void xcd_barrier(const XcdBarrier& b) {
;     asm volatile("s_waitcnt vmcnt(0)" ::: "memory");
;     __syncthreads();
; __global__ void __launch_bounds__(512, 2) mk_fwd(Args args) {
;     ...
;     if (IN(9)) { rotq_rows_i8(WSP(bf16_t, WS_ACT), WSP(unsigned char, WS_ACTQ), WSP(float, WS_SA4), M, F.wave * F.G + (int)blockIdx.x, F.G * 8, F.lane); } SEAM(9);
.LBB0_2804:
	s_cmp_gt_i32 s91, 10
	s_cselect_b64 s[2:3], -1, 0
	s_and_b64 s[0:1], s[0:1], s[2:3]
	s_andn2_b64 vcc, exec, s[0:1]
	s_cbranch_vccnz .LBB0_2858
	s_cmp_lg_u32 s98, 0
	s_cbranch_scc1 .Leinv9
	buffer_inv sc1

; #define SEAM(k) do { if (IN(k) && IN((k) + 1)) xcd_barrier(bar); } while (0)
; __device__ __forceinline__ void xcd_barrier(const XcdBarrier& b) {
;     asm volatile("s_waitcnt vmcnt(0)" ::: "memory");
;     __syncthreads();
; __global__ void __launch_bounds__(512, 2) mk_fwd(Args args) {
;     ...
;             pg8::gemm_phase<EpiPartQ, pg8::GeomSplit, pg8::SplitOrder, true, true>(F.lds, g2, S2, E2); } } SEAM(10);
.LBB0_2888:
	s_cmp_gt_i32 s91, 11
	s_cselect_b64 s[0:1], -1, 0
	s_and_b64 s[2:3], s[6:7], s[0:1]
	s_andn2_b64 vcc, exec, s[2:3]
	s_cbranch_vccnz .LBB0_2942
	s_cmp_lg_u32 s98, 0
	s_cbranch_scc1 .Leinv10
	buffer_inv sc1
